# scan stages 3 and 4 fused: decay products kept in registers with a wave-private exchange, one barrier less per chunk; lane geometry hoisted out of the chunk loop
# speedup vs baseline: 1.0616x; 1.0173x over previous
.LBB0_179:
	s_or_b64 exec, exec, s[4:5]
	s_lshl_b32 s24, s45, 7
	s_add_i32 s14, s20, 0x1000
	s_add_i32 s15, s20, 0x2000
	s_add_i32 s4, s20, 0x7f80
	s_add_i32 s5, s20, 0x9a80
	s_add_i32 s17, s20, 0xc980
	s_add_i32 s23, s20, 0xd280
	s_add_i32 s24, s20, s24
	v_lshlrev_b32_e32 v5, 4, v81
	s_cmp_lg_u32 s45, 0
	v_add_u32_e32 v4, s24, v5
	s_cselect_b64 s[76:77], -1, 0
	s_bitcmp0_b32 s16, 6
	s_mov_b32 s24, 0x8880
	s_waitcnt vmcnt(42)
	v_cvt_pk_f16_f32 v36, v36, v37
	s_waitcnt vmcnt(41)
	v_cvt_pk_f16_f32 v37, v40, v41
	s_waitcnt vmcnt(36)
	v_cvt_pk_f16_f32 v41, v60, v61
	s_cselect_b32 s24, s24, 0x9180
	v_lshlrev_b32_e32 v61, 2, v77
	s_add_i32 s24, s20, s24
	v_cmp_lt_u32_e32 vcc, v61, v130
	v_cvt_pk_f16_f32 v44, v44, v45
	v_cvt_pk_f16_f32 v45, v48, v49
	v_cvt_pk_f16_f32 v48, v52, v53
	v_cvt_pk_f16_f32 v52, v68, v69
	v_cvt_pk_f16_f32 v68, v34, v35
	s_bitcmp0_b32 s16, 7
	v_cndmask_b32_e64 v34, 0, 1, vcc
	v_cmp_le_u32_e32 vcc, v61, v130
	v_cvt_pk_f16_f32 v42, v42, v43
	v_cvt_pk_f16_f32 v43, v46, v47
	v_cndmask_b32_e64 v35, 0, 1, vcc
	s_cselect_b64 vcc, -1, 0
	s_and_b64 s[26:27], vcc, exec
	s_cselect_b32 s25, s4, s5
	s_cmp_eq_u32 s45, 2
	s_mov_b32 s4, 0xcc80
	s_cselect_b32 s4, s4, 0xcf80
	s_add_i32 s16, s20, s4
	s_cmp_eq_u32 s45, 1
	v_cvt_pk_f16_f32 v46, v50, v51
	v_cvt_pk_f16_f32 v51, v70, v71
	v_cndmask_b32_e32 v70, v35, v34, vcc
	s_cselect_b64 s[4:5], -1, 0
	v_mul_u32_u24_e32 v34, 0x48, v130
	s_and_b64 s[26:27], s[4:5], exec
	v_lshlrev_b32_e32 v34, 1, v34
	v_lshlrev_b32_e32 v71, 4, v77
	s_cselect_b32 s14, s14, s15
	s_cselect_b32 s26, s17, s16
	s_cmp_eq_u32 s45, 0
	v_add_u32_e32 v35, s20, v34
	v_add3_u32 v162, s24, v34, v71
	v_add3_u32 v163, s25, v34, v71
	v_mul_u32_u24_e32 v34, 24, v130
	v_cvt_pk_f16_f32 v50, v66, v67
	v_cvt_pk_f16_f32 v66, v22, v23
	v_lshlrev_b32_e32 v155, 3, v77
	s_waitcnt vmcnt(29)
	v_cvt_pk_f16_f32 v22, v75, v86
	s_cselect_b32 s14, s20, s14
	s_cselect_b32 s23, s23, s26
	v_lshlrev_b32_e32 v75, 1, v34
	s_lshl_b64 s[24:25], s[46:47], 1
	v_mov_b32_e32 v60, s20
	v_add3_u32 v164, s23, v75, v155
	s_movk_i32 s23, 0xc0
	s_mul_hi_i32 s60, s18, 0x9000
	s_mul_i32 s61, s18, 0x9000
	s_add_u32 s18, s0, s24
	v_lshl_add_u32 v156, v82, 1, s20
	v_lshl_add_u32 v157, v82, 2, s14
	v_mad_u32_u24 v82, v77, s23, v60
	s_addc_u32 s23, s1, s25
	s_lshl_b32 s19, s19, 1
	v_and_b32_e32 v3, 63, v80
	v_mul_i32_i24_e32 v34, 0xffffffa0, v130
	s_add_u32 s18, s18, s19
	v_cvt_pk_f16_f32 v40, v56, v57
	v_lshrrev_b32_e32 v57, 3, v3
	v_add_u32_e32 v158, v35, v71
	v_add3_u32 v131, v35, v34, v155
	s_addc_u32 s19, s23, 0
	v_lshlrev_b32_e32 v34, 1, v130
	v_mov_b32_e32 v35, v2
	v_cmp_eq_u32_e64 s[14:15], 0, v81
	v_and_b32_e32 v160, 48, v80
	v_lshl_add_u64 v[80:81], s[18:19], 0, v[34:35]
	v_lshl_add_u32 v34, s45, 2, v57
	v_mad_u32_u24 v35, v34, s3, v60
	v_mul_u32_u24_e32 v60, 0x90, v34
	v_mov_b32_e32 v34, -1
	v_add_u32_sdwa v167, v76, v34 dst_sel:DWORD dst_unused:UNUSED_PAD src0_sel:BYTE_0 src1_sel:DWORD
	v_lshlrev_b32_e32 v34, 1, v3
	v_cvt_pk_f16_f32 v47, v62, v63
	v_cvt_f16_f32_e32 v62, v27
	v_cvt_f16_f32_e32 v56, v17
	s_waitcnt vmcnt(16)
	v_cvt_pk_f16_f32 v17, v100, v104
	s_waitcnt vmcnt(8)
	v_cvt_pk_f16_f32 v27, v105, v107
	s_movk_i32 s18, 0xff48
	s_lshl_b32 s46, s22, 11
	v_add_u32_e32 v168, s20, v34
	v_sub_u32_e32 v171, 0, v34
	v_cvt_f32_f16_e32 v104, v36
	v_cvt_f32_f16_sdwa v105, v36 dst_sel:DWORD dst_unused:UNUSED_PAD src0_sel:WORD_1
	v_lshl_or_b32 v34, v77, 10, v74
	v_or_b32_e32 v36, 1, v61
	v_cvt_pk_f16_f32 v38, v38, v39
	v_cvt_pk_f16_f32 v39, v54, v55
	v_mad_i32_i24 v166, v77, s18, v82
	s_add_i32 s46, s46, s21
	v_mad_u32_u24 v169, v3, 48, s20
	s_movk_i32 s18, 0xffd4
	v_cvt_f32_f16_e32 v124, v37
	v_cvt_f32_f16_sdwa v125, v37 dst_sel:DWORD dst_unused:UNUSED_PAD src0_sel:WORD_1
	v_add_u32_e32 v184, s20, v34
	v_lshl_or_b32 v34, v36, 8, v74
	v_or_b32_e32 v37, 2, v61
	v_mad_i32_i24 v170, v3, s18, v169
	v_cvt_f32_f16_e32 v120, v39
	v_cvt_f32_f16_sdwa v121, v39 dst_sel:DWORD dst_unused:UNUSED_PAD src0_sel:WORD_1
	v_add_u32_e32 v186, s20, v34
	v_lshl_or_b32 v34, v37, 8, v74
	v_or_b32_e32 v39, 3, v61
	s_and_b64 s[18:19], s[12:13], exec
	v_cvt_pk_f16_f32 v53, v72, v73
	v_lshlrev_b32_e32 v72, 2, v3
	v_add_u32_e32 v187, s20, v34
	v_lshl_or_b32 v34, v39, 8, v74
	s_cselect_b32 s63, 0, 0xf00
	s_movk_i32 s18, 0xe00
	v_add_u32_e32 v188, s20, v34
	s_cselect_b32 s66, 0x100, s18
	s_movk_i32 s18, 0xd00
	v_or_b32_e32 v34, s63, v72
	s_cselect_b32 s67, 0x200, s18
	s_movk_i32 s18, 0xc00
	v_add_u32_e32 v189, s20, v34
	v_or_b32_e32 v34, s66, v72
	s_cselect_b32 s72, 0x300, s18
	s_movk_i32 s18, 0xb00
	v_add_u32_e32 v190, s20, v34
	v_or_b32_e32 v34, s67, v72
	s_cselect_b32 s73, 0x400, s18
	s_movk_i32 s18, 0x500
	v_add_u32_e32 v191, s20, v34
	v_or_b32_e32 v34, s72, v72
	s_cselect_b32 s74, s18, 0xa00
	s_movk_i32 s18, 0x900
	v_add_u32_e32 v192, s20, v34
	v_or_b32_e32 v34, s73, v72
	s_cselect_b32 s75, 0x600, s18
	s_movk_i32 s18, 0x700
	v_add_u32_e32 v193, s20, v34
	v_or_b32_e32 v34, s74, v72
	s_cselect_b32 s78, s18, 0x800
	v_add_u32_e32 v194, s20, v34
	v_or_b32_e32 v34, s75, v72
	s_movk_i32 s18, 0x1c0
	v_add_u32_e32 v195, s20, v34
	v_or_b32_e32 v34, s78, v72
	s_cselect_b32 s18, 0x200, s18
	v_add_u32_e32 v199, s20, v34
	v_or_b32_e32 v34, s18, v3
	s_movk_i32 s18, 0x240
	s_cselect_b32 s18, s18, 0x180
	v_lshl_add_u32 v200, v34, 2, s20
	v_or_b32_e32 v34, s18, v3
	s_movk_i32 s18, 0x140
	s_cselect_b32 s18, 0x280, s18
	v_lshl_add_u32 v201, v34, 2, s20
	v_or_b32_e32 v34, s18, v3
	s_movk_i32 s18, 0x2c0
	s_cselect_b32 s18, s18, 0x100
	v_lshl_add_u32 v202, v34, 2, s20
	v_or_b32_e32 v34, s18, v3
	s_movk_i32 s18, 0x300
	s_cselect_b32 s18, s18, 0xc0
	v_lshl_add_u32 v203, v34, 2, s20
	v_or_b32_e32 v34, s18, v3
	s_movk_i32 s18, 0x340
	s_cselect_b32 s18, s18, 0x80
	v_lshl_add_u32 v204, v34, 2, s20
	v_or_b32_e32 v34, s18, v3
	s_cselect_b32 s18, 0x380, 64
	v_lshl_add_u32 v205, v34, 2, s20
	v_or_b32_e32 v34, s18, v3
	s_cselect_b32 s18, 0x3c0, 0
	v_lshl_add_u32 v206, v34, 2, s20
	v_or_b32_e32 v34, s18, v3
	v_lshl_add_u32 v207, v34, 2, s20
	s_lshl_b32 s18, s18, 2
	v_and_b32_e32 v34, 1, v70
	v_add_u32_e32 v159, s20, v72
	v_add_u32_e32 v161, s20, v160
	v_mad_u32_u24 v132, v83, 48, s20
	v_add_u32_e32 v172, s20, v75
	v_lshl_add_u32 v182, v57, 2, s20
	v_add_u32_e32 v185, s20, v71
	s_add_i32 s20, s20, s18
	v_cmp_eq_u32_e64 s[18:19], 1, v34
	v_cndmask_b32_e32 v34, v61, v36, vcc
	v_cmp_lt_u32_e64 s[22:23], v37, v130
	v_add_u32_e32 v208, s20, v72
	v_cmp_gt_u32_e64 s[20:21], v130, v34
	v_cndmask_b32_e64 v34, 0, 1, s[22:23]
	v_cmp_le_u32_e64 s[22:23], v37, v130
	v_cvt_f32_f16_e32 v118, v38
	v_cvt_f32_f16_sdwa v119, v38 dst_sel:DWORD dst_unused:UNUSED_PAD src0_sel:WORD_1
	v_cndmask_b32_e64 v38, 0, 1, s[22:23]
	v_cndmask_b32_e32 v34, v38, v34, vcc
	v_and_b32_e32 v34, 1, v34
	v_cmp_lt_u32_e64 s[24:25], v39, v130
	v_cmp_eq_u32_e64 s[22:23], 1, v34
	v_cmp_gt_u32_e64 s[16:17], 32, v3
	v_cndmask_b32_e64 v34, 0, 1, s[24:25]
	v_cmp_le_u32_e64 s[24:25], v39, v130
	v_mul_i32_i24_e32 v76, 0xffffffd2, v3
	v_cmp_gt_u32_e64 s[26:27], 16, v3
	v_cndmask_b32_e64 v38, 0, 1, s[24:25]
	v_cndmask_b32_e32 v34, v38, v34, vcc
	v_and_b32_e32 v34, 1, v34
	v_lshlrev_b32_e32 v3, 12, v77
	v_cmp_eq_u32_e64 s[24:25], 1, v34
	v_xor_b32_e32 v34, 0x3c00, v3
	v_cvt_f16_f32_e32 v116, v26
	v_cvt_f16_f32_e32 v63, v28
	v_cvt_pk_f16_f32 v49, v64, v65
	v_cvt_f16_f32_e32 v64, v29
	v_cvt_f16_f32_e32 v65, v14
	v_cvt_pk_f16_f32 v54, v58, v59
	v_cvt_f16_f32_e32 v55, v15
	v_cvt_f16_f32_e32 v58, v16
	v_cndmask_b32_e64 v34, v34, v3, s[12:13]
	v_xor_b32_e32 v3, 14, v61
	v_cndmask_b32_e64 v3, v3, v36, s[12:13]
	v_lshlrev_b32_e32 v36, 10, v3
	v_xor_b32_e32 v3, 13, v61
	v_cvt_pk_f16_f32 v67, v30, v31
	v_cvt_pk_f16_f32 v59, v24, v25
	v_cvt_pk_f16_f32 v69, v32, v33
	v_cndmask_b32_e64 v3, v3, v37, s[12:13]
	v_cvt_pk_f16_f32 v16, v93, v96
	v_cvt_pk_f16_f32 v15, v89, v91
	v_cvt_pk_f16_f32 v14, v85, v87
	v_cvt_pk_f16_f32 v25, v97, v101
	v_cvt_pk_f16_f32 v24, v92, v94
	v_cvt_pk_f16_f32 v23, v88, v90
	s_waitcnt vmcnt(2)
	v_cvt_pk_f16_f32 v29, v113, v115
	v_cvt_pk_f16_f32 v28, v109, v111
	v_cvt_pk_f16_f32 v26, v98, v102
	s_waitcnt vmcnt(0)
	v_cvt_pk_f16_f32 v33, v112, v114
	v_cvt_pk_f16_f32 v32, v108, v110
	v_cvt_pk_f16_f32 v31, v103, v106
	v_cvt_pk_f16_f32 v30, v95, v99
	v_add_u32_e32 v165, v82, v155
	v_cvt_f32_f16_e32 v82, v42
	v_cvt_f32_f16_sdwa v83, v42 dst_sel:DWORD dst_unused:UNUSED_PAD src0_sel:WORD_1
	v_cvt_f32_f16_e32 v84, v43
	v_cvt_f32_f16_sdwa v85, v43 dst_sel:DWORD dst_unused:UNUSED_PAD src0_sel:WORD_1
	v_cvt_f32_f16_e32 v86, v46
	v_cvt_f32_f16_sdwa v87, v46 dst_sel:DWORD dst_unused:UNUSED_PAD src0_sel:WORD_1
	v_cvt_f32_f16_e32 v88, v44
	v_cvt_f32_f16_sdwa v89, v44 dst_sel:DWORD dst_unused:UNUSED_PAD src0_sel:WORD_1
	v_cvt_f32_f16_e32 v90, v45
	v_cvt_f32_f16_sdwa v91, v45 dst_sel:DWORD dst_unused:UNUSED_PAD src0_sel:WORD_1
	v_cvt_f32_f16_e32 v92, v48
	v_cvt_f32_f16_sdwa v93, v48 dst_sel:DWORD dst_unused:UNUSED_PAD src0_sel:WORD_1
	v_cvt_f32_f16_e32 v94, v66
	v_cvt_f32_f16_sdwa v95, v66 dst_sel:DWORD dst_unused:UNUSED_PAD src0_sel:WORD_1
	v_cvt_f32_f16_e32 v96, v67
	v_cvt_f32_f16_sdwa v97, v67 dst_sel:DWORD dst_unused:UNUSED_PAD src0_sel:WORD_1
	v_cvt_f32_f16_e32 v98, v68
	v_cvt_f32_f16_sdwa v99, v68 dst_sel:DWORD dst_unused:UNUSED_PAD src0_sel:WORD_1
	v_cvt_f32_f16_e32 v100, v59
	v_cvt_f32_f16_sdwa v101, v59 dst_sel:DWORD dst_unused:UNUSED_PAD src0_sel:WORD_1
	v_cvt_f32_f16_e32 v102, v69
	v_cvt_f32_f16_sdwa v103, v69 dst_sel:DWORD dst_unused:UNUSED_PAD src0_sel:WORD_1
	v_cvt_f32_f16_e32 v174, v116
	v_cvt_f32_f16_e32 v175, v62
	v_cvt_f32_f16_e32 v176, v63
	v_cvt_f32_f16_e32 v177, v64
	v_cvt_f32_f16_e32 v178, v65
	v_cvt_f32_f16_e32 v179, v55
	v_cvt_f32_f16_e32 v180, v58
	v_cvt_f32_f16_e32 v181, v56
	v_cvt_f32_f16_e32 v106, v47
	v_cvt_f32_f16_sdwa v107, v47 dst_sel:DWORD dst_unused:UNUSED_PAD src0_sel:WORD_1
	v_cvt_f32_f16_e32 v108, v50
	v_cvt_f32_f16_sdwa v109, v50 dst_sel:DWORD dst_unused:UNUSED_PAD src0_sel:WORD_1
	v_cvt_f32_f16_e32 v110, v51
	v_cvt_f32_f16_sdwa v111, v51 dst_sel:DWORD dst_unused:UNUSED_PAD src0_sel:WORD_1
	v_cvt_f32_f16_e32 v112, v49
	v_cvt_f32_f16_sdwa v113, v49 dst_sel:DWORD dst_unused:UNUSED_PAD src0_sel:WORD_1
	v_cvt_f32_f16_e32 v114, v52
	v_cvt_f32_f16_sdwa v115, v52 dst_sel:DWORD dst_unused:UNUSED_PAD src0_sel:WORD_1
	v_cvt_f32_f16_e32 v116, v53
	v_cvt_f32_f16_sdwa v117, v53 dst_sel:DWORD dst_unused:UNUSED_PAD src0_sel:WORD_1
	v_cvt_f32_f16_e32 v122, v54
	v_cvt_f32_f16_sdwa v123, v54 dst_sel:DWORD dst_unused:UNUSED_PAD src0_sel:WORD_1
	v_cvt_f32_f16_e32 v126, v40
	v_cvt_f32_f16_sdwa v127, v40 dst_sel:DWORD dst_unused:UNUSED_PAD src0_sel:WORD_1
	v_cvt_f32_f16_e32 v128, v41
	v_cvt_f32_f16_sdwa v129, v41 dst_sel:DWORD dst_unused:UNUSED_PAD src0_sel:WORD_1
	v_lshlrev_b32_e32 v38, 10, v3
	v_xor_b32_e32 v3, 12, v61
	v_lshlrev_b32_e32 v173, 8, v57
	v_cndmask_b32_e64 v3, v3, v39, s[12:13]
	v_sub_u32_e32 v73, 0, v155
	v_mul_u32_u24_e32 v133, 0x280, v57
	v_or_b32_e32 v42, 0x800, v173
	v_lshlrev_b32_e32 v40, 10, v3
	v_mov_b32_e32 v46, 0
	s_mov_b32 s57, 0
	s_mov_b32 s62, 16
	v_mul_u32_u24_e32 v183, 0x90, v57
	v_cmp_eq_u32_e64 s[28:29], 1, v77
	v_cmp_eq_u32_e64 s[30:31], 2, v77
	v_cmp_eq_u32_e64 s[34:35], 3, v77
	v_add_u32_e32 v209, v166, v75
	v_add_u32_e32 v210, v161, v75
	s_movk_i32 s79, 0x8e0
	v_add_u32_e32 v211, v157, v42
	v_add_u32_e32 v212, v35, v5
	v_add_u32_e32 v213, v156, v60
	v_add_u32_e32 v214, v169, v76
	v_add_u32_e32 v215, v158, v73
	v_add_u32_e32 v216, v132, v160
	v_lshlrev_b32_e32 v130, 1, v34
	v_lshlrev_b32_e32 v132, 1, v36
	v_lshlrev_b32_e32 v134, 1, v38
	v_lshlrev_b32_e32 v136, 1, v40
	v_add_u32_e32 v217, v4, v133
	v_add_u32_e32 v218, 0x80, v131
	v_mov_b32_e32 v47, v46
	v_mov_b32_e32 v48, v46
	v_mov_b32_e32 v49, v46
	v_mov_b32_e32 v56, v46
	v_mov_b32_e32 v57, v46
	v_mov_b32_e32 v64, v46
	v_mov_b32_e32 v65, v46
	v_mov_b32_e32 v54, v46
	v_mov_b32_e32 v55, v46
	v_mov_b32_e32 v62, v46
	v_mov_b32_e32 v63, v46
	v_mov_b32_e32 v50, v46
	v_mov_b32_e32 v51, v46
	v_mov_b32_e32 v52, v46
	v_mov_b32_e32 v53, v46
	s_mov_b32 s78, 0xbfb8aa3b
	v_mul_f32_e32 v194, s78, v1
	v_mul_f32_e32 v195, s78, v149
	v_and_b32_e32 v219, 15, v235
	v_lshrrev_b32_e32 v220, 4, v235
	v_sub_u32_e32 v221, 3, v220
	v_cndmask_b32_e64 v221, v221, v220, s[12:13]
	s_lshl_b32 s72, s45, 4
	v_add_u32_e32 v222, s72, v219
	v_lshlrev_b32_e32 v223, 2, v235
	v_sub_u32_e32 v223, v170, v223
	v_mul_u32_u24_e32 v189, 0x240, v221
	v_lshl_add_u32 v189, v222, 1, v189
	v_add_u32_e32 v189, v223, v189
	v_mul_u32_u24_e32 v190, 48, v222
	v_lshl_add_u32 v190, v221, 3, v190
	v_add_u32_e32 v190, v223, v190
	s_lshl_b32 s72, s45, 8
	v_lshl_add_u32 v191, v219, 4, s72
	v_add_u32_e32 v191, v223, v191
	v_lshl_add_u32 v192, v220, 2, v191
	v_lshl_add_u32 v193, v222, 2, v223
	v_and_b32_e32 v3, 1, v221
	v_cmp_ne_u32_e64 s[72:73], 0, v3
	v_and_b32_e32 v4, 2, v221
	v_cmp_ne_u32_e64 s[74:75], 0, v4
	s_waitcnt lgkmcnt(0)
	s_barrier
	s_branch .LBB0_181

.LBB0_201:
	s_or_b64 exec, exec, s[88:89]
	s_waitcnt lgkmcnt(0)
	s_barrier
	ds_read_b128 v[34:37], v158 offset:16384
	ds_read_b128 v[38:41], v158 offset:18688
	ds_read_b128 v[42:45], v158 offset:16448
	ds_read_b128 v[238:241], v158 offset:18752
	ds_read_b32 v74, v184 offset:4096
	ds_read_b32 v75, v186 offset:4096
	ds_read_b32 v76, v187 offset:4096
	ds_read_b32 v77, v188 offset:4096
	ds_read2st64_b32 v[138:139], v184 offset1:32
	ds_read2st64_b32 v[140:141], v186 offset1:32
	ds_read2st64_b32 v[142:143], v187 offset1:32
	ds_read2st64_b32 v[144:145], v188 offset1:32
	ds_read_b128 v[58:61], v185 offset:20992
	s_cmpk_eq_i32 s62, 0x900
	s_cselect_b64 s[88:89], -1, 0
	s_waitcnt lgkmcnt(11)
	v_mfma_f32_16x16x32_f16 v[66:69], v[34:37], v[14:17], 0
	v_mfma_f32_16x16x32_f16 v[70:73], v[38:41], v[22:25], 0
	s_waitcnt lgkmcnt(9)
	v_mfma_f32_16x16x32_f16 v[66:69], v[42:45], v[26:29], v[66:69]
	v_mfma_f32_16x16x32_f16 v[70:73], v[238:241], v[30:33], v[70:73]
	s_and_b64 vcc, exec, s[88:89]
	s_cbranch_vccnz .LBB0_217
	s_cmp_gt_u32 s57, 14
	s_mov_b64 s[48:49], -1
	s_cbranch_scc0 .LBB0_204
	s_add_i32 s52, s62, 0xffffff00
	s_and_b64 s[48:49], s[12:13], exec
	s_cselect_b32 s84, s52, s79
	s_mov_b64 s[48:49], 0

.LBB0_217:
	s_nop 7
	s_waitcnt lgkmcnt(0)
	v_fma_f32 v42, v66, s78, v194
	v_fma_f32 v43, v67, s78, v194
	v_fma_f32 v44, v68, s78, v194
	v_fma_f32 v45, v69, s78, v194
	v_fma_f32 v38, v70, s78, v195
	v_fma_f32 v39, v71, s78, v195
	v_fma_f32 v40, v72, s78, v195
	v_fma_f32 v41, v73, s78, v195
	v_exp_f32_e32 v42, v42
	v_exp_f32_e32 v43, v43
	v_exp_f32_e32 v44, v44
	v_exp_f32_e32 v45, v45
	v_exp_f32_e32 v38, v38
	v_exp_f32_e32 v39, v39
	v_exp_f32_e32 v40, v40
	v_exp_f32_e32 v41, v41
	v_add_f32_e32 v42, 1.0, v42
	v_add_f32_e32 v43, 1.0, v43
	v_add_f32_e32 v44, 1.0, v44
	v_add_f32_e32 v45, 1.0, v45
	v_add_f32_e32 v38, 1.0, v38
	v_add_f32_e32 v39, 1.0, v39
	v_add_f32_e32 v40, 1.0, v40
	v_add_f32_e32 v41, 1.0, v41
	v_rcp_f32_e32 v42, v42
	v_rcp_f32_e32 v43, v43
	v_rcp_f32_e32 v44, v44
	v_rcp_f32_e32 v45, v45
	v_rcp_f32_e32 v38, v38
	v_rcp_f32_e32 v39, v39
	v_rcp_f32_e32 v40, v40
	v_rcp_f32_e32 v41, v41
	v_mul_f32_e32 v246, v152, v74
	v_mul_f32_e32 v247, v152, v75
	v_mul_f32_e32 v248, v152, v76
	v_mul_f32_e32 v249, v152, v77
	v_mul_f32_e32 v42, 0xbf60028a, v42
	v_mul_f32_e32 v43, 0xbf60028a, v43
	v_mul_f32_e32 v44, 0xbf60028a, v44
	v_mul_f32_e32 v45, 0xbf60028a, v45
	v_mul_f32_e32 v246, v246, v58
	v_mul_f32_e32 v247, v247, v59
	v_mul_f32_e32 v248, v248, v60
	v_mul_f32_e32 v249, v249, v61
	v_add_f32_e32 v34, -1.0, v38
	v_add_f32_e32 v35, -1.0, v39
	v_add_f32_e32 v36, -1.0, v40
	v_add_f32_e32 v37, -1.0, v41
	v_exp_f32_e32 v242, v42
	v_exp_f32_e32 v243, v43
	v_exp_f32_e32 v244, v44
	v_exp_f32_e32 v245, v45
	v_fma_f32 v34, v153, v34, 1.0
	v_fma_f32 v35, v153, v35, 1.0
	v_fma_f32 v36, v153, v36, 1.0
	v_fma_f32 v37, v153, v37, 1.0
	v_mul_f32_e32 v250, v246, v38
	v_mul_f32_e32 v251, v247, v39
	v_mul_f32_e32 v252, v248, v40
	v_mul_f32_e32 v236, v249, v41
	v_mul_f32_e32 v34, v74, v34
	v_mul_f32_e32 v35, v75, v35
	v_mul_f32_e32 v36, v76, v36
	v_mul_f32_e32 v37, v77, v37
	v_mul_f32_e32 v3, v242, v243
	v_mul_f32_e32 v4, v244, v245
	v_mul_f32_e32 v3, v3, v4
	ds_write_b32 v192, v3 offset:25216
	ds_read_b128 v[58:61], v191 offset:25216
	s_andn2_b64 vcc, exec, s[12:13]
	s_waitcnt lgkmcnt(0)
	s_cbranch_vccnz .Ls34_rev
	v_mul_f32_e32 v5, v58, v59
	s_nop 0
	v_rcp_f32_e32 v66, v5
	s_nop 0
	v_mul_f32_e32 v67, v66, v58
	v_mul_f32_e32 v68, v67, v59
	v_mul_f32_e32 v69, v68, v60
	v_mul_f32_e32 v70, v69, v61
	v_cndmask_b32_e64 v71, v66, v67, s[72:73]
	v_cndmask_b32_e64 v72, v68, v69, s[72:73]
	v_cndmask_b32_e64 v71, v71, v72, s[74:75]
	v_mul_f32_e32 v72, v71, v242
	v_mul_f32_e32 v73, v72, v243
	v_mul_f32_e32 v74, v73, v244
	v_mul_f32_e32 v75, v74, v245
	v_rcp_f32_e32 v38, v72
	v_rcp_f32_e32 v39, v73
	v_rcp_f32_e32 v40, v74
	v_rcp_f32_e32 v41, v75
	v_fma_mixlo_f16 v42, v71, v246, 0
	v_fma_mixhi_f16 v42, v72, v247, 0
	v_fma_mixlo_f16 v43, v73, v248, 0
	v_fma_mixhi_f16 v43, v74, v249, 0
	v_fma_mixlo_f16 v44, v250, v38, 0
	v_fma_mixhi_f16 v44, v251, v39, 0
	v_fma_mixlo_f16 v45, v252, v40, 0
	v_fma_mixhi_f16 v45, v236, v41, 0
	v_fma_mixlo_f16 v238, v34, v38, 0
	v_fma_mixhi_f16 v238, v35, v39, 0
	v_fma_mixlo_f16 v239, v36, v40, 0
	v_fma_mixhi_f16 v239, v37, v41, 0
	v_fma_mixlo_f16 v240, v72, v138, 0
	v_fma_mixhi_f16 v240, v73, v140, 0
	v_fma_mixlo_f16 v241, v74, v142, 0
	v_fma_mixhi_f16 v241, v75, v144, 0
	v_cvt_pk_f16_f32 v146, v139, v141
	v_cvt_pk_f16_f32 v147, v143, v145
	s_mov_b32 s76, 0x80008000
	v_xor_b32_e32 v76, s76, v44
	v_xor_b32_e32 v77, s76, v45
	ds_write_b16 v189, v42 offset:32640
	ds_write_b16_d16_hi v189, v42 offset:32784
	ds_write_b16 v189, v43 offset:32928
	ds_write_b16_d16_hi v189, v43 offset:33072
	ds_write_b16 v189, v44 offset:34944
	ds_write_b16_d16_hi v189, v44 offset:35088
	ds_write_b16 v189, v45 offset:35232
	ds_write_b16_d16_hi v189, v45 offset:35376
	ds_write_b16 v189, v238 offset:37248
	ds_write_b16_d16_hi v189, v238 offset:37392
	ds_write_b16 v189, v239 offset:37536
	ds_write_b16_d16_hi v189, v239 offset:37680
	ds_write_b16 v189, v240 offset:39552
	ds_write_b16_d16_hi v189, v240 offset:39696
	ds_write_b16 v189, v241 offset:39840
	ds_write_b16_d16_hi v189, v241 offset:39984
	ds_write_b64 v190, v[76:77] offset:41856
	ds_write_b64 v190, v[238:239] offset:44928
	ds_write_b64 v190, v[146:147] offset:48000
	s_mov_b64 s[76:77], exec
	s_mov_b64 exec, 0xffff
	ds_write_b32 v193, v5 offset:51072
	ds_write_b32 v193, v70 offset:51328
	s_mov_b64 exec, s[76:77]
	s_branch .LBB0_229
.Ls34_rev:
	v_mul_f32_e32 v5, v61, v60
	s_nop 0
	v_rcp_f32_e32 v66, v5
	s_nop 0
	v_mul_f32_e32 v67, v66, v61
	v_mul_f32_e32 v68, v67, v60
	v_mul_f32_e32 v69, v68, v59
	v_mul_f32_e32 v70, v69, v58
	v_cndmask_b32_e64 v71, v66, v67, s[72:73]
	v_cndmask_b32_e64 v72, v68, v69, s[72:73]
	v_cndmask_b32_e64 v71, v71, v72, s[74:75]
	v_mul_f32_e32 v72, v71, v245
	v_mul_f32_e32 v73, v72, v244
	v_mul_f32_e32 v74, v73, v243
	v_mul_f32_e32 v75, v74, v242
	v_rcp_f32_e32 v38, v72
	v_rcp_f32_e32 v39, v73
	v_rcp_f32_e32 v40, v74
	v_rcp_f32_e32 v41, v75
	v_fma_mixlo_f16 v42, v71, v249, 0
	v_fma_mixhi_f16 v42, v72, v248, 0
	v_fma_mixlo_f16 v43, v73, v247, 0
	v_fma_mixhi_f16 v43, v74, v246, 0
	v_fma_mixlo_f16 v44, v236, v38, 0
	v_fma_mixhi_f16 v44, v252, v39, 0
	v_fma_mixlo_f16 v45, v251, v40, 0
	v_fma_mixhi_f16 v45, v250, v41, 0
	v_fma_mixlo_f16 v238, v37, v38, 0
	v_fma_mixhi_f16 v238, v36, v39, 0
	v_fma_mixlo_f16 v239, v35, v40, 0
	v_fma_mixhi_f16 v239, v34, v41, 0
	v_fma_mixlo_f16 v240, v72, v144, 0
	v_fma_mixhi_f16 v240, v73, v142, 0
	v_fma_mixlo_f16 v241, v74, v140, 0
	v_fma_mixhi_f16 v241, v75, v138, 0
	v_cvt_pk_f16_f32 v146, v145, v143
	v_cvt_pk_f16_f32 v147, v141, v139
	s_mov_b32 s76, 0x80008000
	v_xor_b32_e32 v76, s76, v44
	v_xor_b32_e32 v77, s76, v45
	ds_write_b16 v189, v42 offset:32640
	ds_write_b16_d16_hi v189, v42 offset:32784
	ds_write_b16 v189, v43 offset:32928
	ds_write_b16_d16_hi v189, v43 offset:33072
	ds_write_b16 v189, v44 offset:34944
	ds_write_b16_d16_hi v189, v44 offset:35088
	ds_write_b16 v189, v45 offset:35232
	ds_write_b16_d16_hi v189, v45 offset:35376
	ds_write_b16 v189, v238 offset:37248
	ds_write_b16_d16_hi v189, v238 offset:37392
	ds_write_b16 v189, v239 offset:37536
	ds_write_b16_d16_hi v189, v239 offset:37680
	ds_write_b16 v189, v240 offset:39552
	ds_write_b16_d16_hi v189, v240 offset:39696
	ds_write_b16 v189, v241 offset:39840
	ds_write_b16_d16_hi v189, v241 offset:39984
	ds_write_b64 v190, v[76:77] offset:41856
	ds_write_b64 v190, v[238:239] offset:44928
	ds_write_b64 v190, v[146:147] offset:48000
	s_mov_b64 s[76:77], exec
	s_mov_b64 exec, 0xffff
	ds_write_b32 v193, v5 offset:51072
	ds_write_b32 v193, v70 offset:51328
	s_mov_b64 exec, s[76:77]
